# P0 row loop: hoist loop-invariant fbias load, drop in-loop vmcnt(0)
# speedup vs baseline: 1.0038x; 1.0038x over previous
; #define LAS __attribute__((address_space(3)))
; __device__ __forceinline__ unsigned pk2(float lo, float hi) { return f2bf(lo) | (f2bf(hi) << 16); }
; __device__ __forceinline__ float log_sigmoid(float y) { return fminf(y, 0.f) - log1pf(expf(-fabsf(y))); }
; __global__ void __launch_bounds__(NWAVES * 64, 2) fwd_megakernel(Args args) {
;     ...
;         f32x4 gv[4];
; #pragma unroll
;         for (int j = 0; j < 4; ++j) gv[j] = ((const f32x4*)attn_g)[lane + 64 * j];
;         f32x4 vn[4];
;         if (gw < MROWS) { const f32x4* xr = (const f32x4*)(x + (size_t)gw * DMODEL) + lane;
; #pragma unroll
;             for (int j = 0; j < 4; ++j) vn[j] = __builtin_nontemporal_load(xr + 64 * j); }
;         for (int m = gw; m < MROWS; m += NGW) {
;             f32x4 v[4]; float s2 = 0.f;
; #pragma unroll
;             for (int j = 0; j < 4; ++j) { v[j] = vn[j]; s2 += (v[j].x * v[j].x + v[j].y * v[j].y) + (v[j].z * v[j].z + v[j].w * v[j].w); }
;             if (m + NGW < MROWS) { const f32x4* xr = (const f32x4*)(x + (size_t)(m + NGW) * DMODEL) + lane;
; #pragma unroll
;                 for (int j = 0; j < 4; ++j) vn[j] = __builtin_nontemporal_load(xr + 64 * j); }
;             const float rstd = 1.0f / sqrtf(wave_sum(s2) * (1.0f / DMODEL) + RMS_EPS);
;             unsigned long long* o8 = (unsigned long long*)(XN + (size_t)m * DMODEL) + lane;
;             float fa[8];
; #pragma unroll
;             for (int e = 0; e < 8; ++e) fa[e] = 0.f;
; #pragma unroll
;             for (int j = 0; j < 4; ++j) { v[j] = v[j] * rstd * gv[j];
;                 o8[64 * j] = (unsigned long long)pk2(v[j].x, v[j].y) | ((unsigned long long)pk2(v[j].z, v[j].w) << 32);
; #pragma unroll
;                 for (int i = 0; i < 4; ++i) { const int k = 256 * j + 4 * lane + i; const f32x4 wa = *(const LAS f32x4*)(Wf + k * 8), wb = *(const LAS f32x4*)(Wf + k * 8 + 4); const float hk = v[j][i];
;                     fa[0] += hk * wa[0]; fa[1] += hk * wa[1]; fa[2] += hk * wa[2]; fa[3] += hk * wa[3]; fa[4] += hk * wb[0]; fa[5] += hk * wb[1]; fa[6] += hk * wb[2]; fa[7] += hk * wb[3]; } }
;     ...
;             if ((lane & 7) == 0) { const int e = lane >> 3; LF[(size_t)m * 8 + e] = log_sigmoid(r1 + fbias[e]); }
.LBB0_171:
	s_or_b64 exec, exec, s[0:1]
	s_cmp_lt_i32 s62, 0x8000
	s_cselect_b64 s[0:1], -1, 0
	v_mov_b32_e32 v83, 0
	v_writelane_b32 v249, s0, 19
	s_and_b64 vcc, exec, s[0:1]
	v_mbcnt_lo_u32_b32 v1, -1, 0
	s_waitcnt lgkmcnt(0)
	s_barrier
	v_writelane_b32 v249, s1, 20
	s_cbranch_vccz .LBB0_178
	s_ashr_i32 s63, s62, 31
	s_lshl_b64 s[0:1], s[62:63], 12
	s_add_u32 s0, s72, s0
	v_lshlrev_b32_e32 v82, 4, v180
	s_addc_u32 s1, s73, s1
	global_load_dwordx4 v[2:5], v82, s[74:75] offset:3072
	global_load_dwordx4 v[6:9], v82, s[74:75] offset:2048
	global_load_dwordx4 v[10:13], v82, s[74:75] offset:1024
	global_load_dwordx4 v[14:17], v82, s[74:75]
	global_load_dwordx4 v[174:177], v82, s[0:1] nt
	global_load_dwordx4 v[170:173], v82, s[0:1] offset:1024 nt
	global_load_dwordx4 v[166:169], v82, s[0:1] offset:2048 nt
	global_load_dwordx4 v[162:165], v82, s[0:1] offset:3072 nt
	v_mbcnt_hi_u32_b32 v18, -1, v1
	v_and_b32_e32 v19, 64, v18
	v_add_u32_e32 v19, 64, v19
	v_xor_b32_e32 v20, 1, v18
	v_cmp_lt_i32_e32 vcc, v20, v19
	s_lshl_b64 s[12:13], s[62:63], 11
	v_mov_b32_e32 v85, v83
	v_cndmask_b32_e32 v20, v18, v20, vcc
	v_lshlrev_b32_e32 v179, 2, v20
	v_xor_b32_e32 v20, 2, v18
	v_cmp_lt_i32_e32 vcc, v20, v19
	s_lshl_b64 s[10:11], s[62:63], 5
	v_lshl_or_b32 v190, v180, 3, s12
	v_cndmask_b32_e32 v20, v18, v20, vcc
	v_lshlrev_b32_e32 v197, 2, v20
	v_xor_b32_e32 v20, 4, v18
	v_cmp_lt_i32_e32 vcc, v20, v19
	s_add_i32 s12, s62, s64
	s_ashr_i32 s65, s64, 31
	v_cndmask_b32_e32 v20, v18, v20, vcc
	v_lshlrev_b32_e32 v198, 2, v20
	v_xor_b32_e32 v20, 8, v18
	v_cmp_lt_i32_e32 vcc, v20, v19
	v_mov_b32_e32 v191, s13
	s_ashr_i32 s13, s12, 31
	v_cndmask_b32_e32 v20, v18, v20, vcc
	v_lshlrev_b32_e32 v199, 2, v20
	v_xor_b32_e32 v20, 16, v18
	v_cmp_lt_i32_e32 vcc, v20, v19
	s_lshl_b64 s[14:15], s[64:65], 11
	s_lshl_b64 s[12:13], s[12:13], 12
	v_cndmask_b32_e32 v20, v18, v20, vcc
	v_lshlrev_b32_e32 v200, 2, v20
	v_xor_b32_e32 v20, 32, v18
	v_cmp_lt_i32_e32 vcc, v20, v19
	v_lshl_add_u32 v142, v180, 7, 0
	v_cmp_eq_u32_e64 s[8:9], 0, v184
	v_cndmask_b32_e32 v18, v18, v20, vcc
	v_lshlrev_b32_e32 v201, 2, v18
	v_and_b32_e32 v18, 32, v178
	v_cmp_eq_u32_e64 s[0:1], 0, v18
	v_and_b32_e32 v18, 16, v178
	v_cmp_eq_u32_e64 s[4:5], 0, v18
	v_and_b32_e32 v18, 8, v178
	v_cmp_eq_u32_e64 s[6:7], 0, v18
	v_lshrrev_b32_e32 v18, 1, v180
	v_and_b32_e32 v84, 28, v18
	v_lshl_add_u64 v[186:187], s[78:79], 0, v[84:85]
	global_load_dword v214, v[186:187], off
	v_or_b32_e32 v84, s10, v84
	v_mov_b32_e32 v85, s11
	s_mov_b64 s[10:11], 0x1a00000
	v_lshl_add_u64 v[188:189], v[84:85], 0, s[10:11]
	s_lshl_b64 s[10:11], s[64:65], 5
	s_add_u32 s12, s72, s12
	s_addc_u32 s13, s73, s13
	v_lshl_add_u64 v[82:83], s[12:13], 0, v[82:83]
	s_mov_b64 s[12:13], 0x800
	v_lshl_add_u64 v[192:193], v[82:83], 0, s[12:13]
	ds_read_b128 v[18:21], v142
	ds_read_b128 v[22:25], v142 offset:16
	ds_read_b128 v[26:29], v142 offset:32
	ds_read_b128 v[30:33], v142 offset:48
	ds_read_b128 v[34:37], v142 offset:64
	ds_read_b128 v[38:41], v142 offset:80
	ds_read_b128 v[42:45], v142 offset:96
	ds_read_b128 v[46:49], v142 offset:112
	ds_read_b128 v[50:53], v142 offset:8192
	ds_read_b128 v[54:57], v142 offset:8208
	ds_read_b128 v[58:61], v142 offset:8224
	ds_read_b128 v[62:65], v142 offset:8240
	ds_read_b128 v[66:69], v142 offset:8256
	ds_read_b128 v[70:73], v142 offset:8272
	ds_read_b128 v[74:77], v142 offset:8288
	ds_read_b128 v[78:81], v142 offset:8304
	ds_read_b128 v[82:85], v142 offset:16384
	ds_read_b128 v[86:89], v142 offset:16400
	ds_read_b128 v[90:93], v142 offset:16416
	ds_read_b128 v[94:97], v142 offset:16432
	ds_read_b128 v[98:101], v142 offset:16448
	ds_read_b128 v[102:105], v142 offset:16464
	ds_read_b128 v[106:109], v142 offset:16480
	ds_read_b128 v[110:113], v142 offset:16496
	ds_read_b128 v[114:117], v142 offset:24576
	ds_read_b128 v[118:121], v142 offset:24592
	ds_read_b128 v[122:125], v142 offset:24608
	ds_read_b128 v[126:129], v142 offset:24624
	ds_read_b128 v[130:133], v142 offset:24640
	ds_read_b128 v[134:137], v142 offset:24656
	ds_read_b128 v[138:141], v142 offset:24672
	ds_read_b128 v[142:145], v142 offset:24688
	s_lshl_b64 s[16:17], s[64:65], 12
	s_movk_i32 s20, 0x7fff
	v_mov_b32_e32 v202, 0x358637bd
	s_mov_b32 s21, 0xf800000
	v_mov_b32_e32 v203, 0x260
	s_mov_b32 s22, 0xffff0000
	s_mov_b32 s23, 0x3000000
	s_mov_b32 s26, 0xbfb8aa3b
	s_mov_b32 s27, 0xb2a5705f
	s_mov_b32 s28, 0x42ce8ed0
	s_mov_b32 s29, 0xc2b17218
	s_mov_b32 s30, 0x7f800000
	s_mov_b32 s31, 0x3f2aaaab
	v_mov_b32_e32 v204, 0x3ecc95a3
	s_mov_b32 s33, 0x3f317218
	s_mov_b32 s34, 0x33800000
	s_waitcnt vmcnt(3)
	v_mov_b64_e32 v[146:147], v[174:175]
	s_waitcnt vmcnt(2)
	v_mov_b64_e32 v[150:151], v[170:171]
	s_waitcnt vmcnt(1)
	v_mov_b64_e32 v[154:155], v[166:167]
	s_waitcnt vmcnt(0)
	v_mov_b64_e32 v[158:159], v[162:163]
	v_mov_b32_e32 v205, 0x7f800000
	v_mov_b32_e32 v194, 0x3f317218
	s_mov_b32 s35, s62
	v_mov_b64_e32 v[148:149], v[176:177]
	v_mov_b64_e32 v[152:153], v[172:173]
	v_mov_b64_e32 v[156:157], v[168:169]
	v_mov_b64_e32 v[160:161], v[164:165]
	s_branch .LBB0_174

; #define LAS __attribute__((address_space(3)))
; __device__ __forceinline__ unsigned pk2(float lo, float hi) { return f2bf(lo) | (f2bf(hi) << 16); }
; __global__ void __launch_bounds__(NWAVES * 64, 2) fwd_megakernel(Args args) {
;     ...
;             f32x4 v[4]; float s2 = 0.f;
; #pragma unroll
;             for (int j = 0; j < 4; ++j) { v[j] = vn[j]; s2 += (v[j].x * v[j].x + v[j].y * v[j].y) + (v[j].z * v[j].z + v[j].w * v[j].w); }
;             if (m + NGW < MROWS) { const f32x4* xr = (const f32x4*)(x + (size_t)(m + NGW) * DMODEL) + lane;
; #pragma unroll
;                 for (int j = 0; j < 4; ++j) vn[j] = __builtin_nontemporal_load(xr + 64 * j); }
;             const float rstd = 1.0f / sqrtf(wave_sum(s2) * (1.0f / DMODEL) + RMS_EPS);
;             unsigned long long* o8 = (unsigned long long*)(XN + (size_t)m * DMODEL) + lane;
;             float fa[8];
; #pragma unroll
;             for (int e = 0; e < 8; ++e) fa[e] = 0.f;
; #pragma unroll
;             for (int j = 0; j < 4; ++j) { v[j] = v[j] * rstd * gv[j];
;                 o8[64 * j] = (unsigned long long)pk2(v[j].x, v[j].y) | ((unsigned long long)pk2(v[j].z, v[j].w) << 32);
; #pragma unroll
;                 for (int i = 0; i < 4; ++i) { const int k = 256 * j + 4 * lane + i; const f32x4 wa = *(const LAS f32x4*)(Wf + k * 8), wb = *(const LAS f32x4*)(Wf + k * 8 + 4); const float hk = v[j][i];
;                     fa[0] += hk * wa[0]; fa[1] += hk * wa[1]; fa[2] += hk * wa[2]; fa[3] += hk * wa[3]; fa[4] += hk * wb[0]; fa[5] += hk * wb[1]; fa[6] += hk * wb[2]; fa[7] += hk * wb[3]; } }
.LBB0_176:
	v_mul_f32_e32 v195, v175, v175
	v_mul_f32_e32 v196, v177, v177
	v_fmac_f32_e32 v195, v174, v174
	v_fmac_f32_e32 v196, v176, v176
	v_add_f32_e32 v195, v195, v196
	v_mul_f32_e32 v196, v171, v171
	v_mul_f32_e32 v206, v173, v173
	v_fmac_f32_e32 v196, v170, v170
	v_fmac_f32_e32 v206, v172, v172
	v_add_f32_e32 v196, v196, v206
	v_add_f32_e32 v195, v195, v196
	v_mul_f32_e32 v196, v167, v167
	v_mul_f32_e32 v206, v169, v169
	v_fmac_f32_e32 v196, v166, v166
	v_fmac_f32_e32 v206, v168, v168
	v_add_f32_e32 v196, v196, v206
	v_add_f32_e32 v195, v195, v196
	v_mul_f32_e32 v196, v163, v163
	v_mul_f32_e32 v206, v165, v165
	v_fmac_f32_e32 v196, v162, v162
	v_fmac_f32_e32 v206, v164, v164
	v_add_f32_e32 v196, v196, v206
	v_add_f32_e32 v195, v195, v196
	ds_bpermute_b32 v196, v179, v195
	s_waitcnt lgkmcnt(0)
	v_add_f32_e32 v195, v195, v196
	ds_bpermute_b32 v196, v197, v195
	s_waitcnt lgkmcnt(0)
	v_add_f32_e32 v195, v195, v196
	ds_bpermute_b32 v196, v198, v195
	s_waitcnt lgkmcnt(0)
	v_add_f32_e32 v195, v195, v196
	ds_bpermute_b32 v196, v199, v195
	s_waitcnt lgkmcnt(0)
	v_add_f32_e32 v195, v195, v196
	ds_bpermute_b32 v196, v200, v195
	s_waitcnt lgkmcnt(0)
	v_add_f32_e32 v195, v195, v196
	ds_bpermute_b32 v196, v201, v195
	s_waitcnt lgkmcnt(0)
	v_add_f32_e32 v195, v195, v196
	v_fmamk_f32 v195, v195, 0x3a800000, v202
	v_mul_f32_e32 v196, 0x4f800000, v195
	v_cmp_gt_f32_e32 vcc, s21, v195
	s_nop 1
	v_cndmask_b32_e32 v195, v195, v196, vcc
	v_sqrt_f32_e32 v196, v195
	s_nop 0
	v_add_u32_e32 v206, -1, v196
	v_add_u32_e32 v207, 1, v196
	v_fma_f32 v208, -v206, v196, v195
	v_fma_f32 v209, -v207, v196, v195
	v_cmp_ge_f32_e64 s[12:13], 0, v208
	s_nop 1
	v_cndmask_b32_e64 v196, v196, v206, s[12:13]
	v_cmp_lt_f32_e64 s[12:13], 0, v209
	s_nop 1
	v_cndmask_b32_e64 v196, v196, v207, s[12:13]
	v_mul_f32_e32 v206, 0x37800000, v196
	v_cndmask_b32_e32 v196, v196, v206, vcc
	v_cmp_class_f32_e32 vcc, v195, v203
	v_lshl_add_u64 v[206:207], s[66:67], 0, v[190:191]
	s_nop 0
	v_cndmask_b32_e32 v195, v196, v195, vcc
	v_div_scale_f32 v196, s[12:13], v195, v195, 1.0
	v_rcp_f32_e32 v208, v196
	v_div_scale_f32 v209, vcc, 1.0, v195, 1.0
	v_fma_f32 v210, -v196, v208, 1.0
	v_fmac_f32_e32 v208, v210, v208
	v_mul_f32_e32 v210, v209, v208
	v_fma_f32 v211, -v196, v210, v209
	v_fmac_f32_e32 v210, v211, v208
	v_fma_f32 v196, -v196, v210, v209
	v_div_fmas_f32 v196, v196, v208, v210
	v_div_fixup_f32 v196, v196, v195, 1.0
	v_pk_mul_f32 v[174:175], v[196:197], v[174:175] op_sel_hi:[0,1]
	v_pk_mul_f32 v[208:209], v[174:175], v[14:15]
	v_pk_mul_f32 v[176:177], v[196:197], v[176:177] op_sel_hi:[0,1]
	v_bfe_u32 v174, v208, 16, 1
	v_add3_u32 v174, v208, v174, s20
	v_bfe_u32 v175, v209, 16, 1
	v_pk_mul_f32 v[176:177], v[176:177], v[16:17]
	v_lshrrev_b32_e32 v174, 16, v174
	v_add3_u32 v175, v209, v175, s20
	v_and_or_b32 v210, v175, s22, v174
	v_bfe_u32 v174, v176, 16, 1
	v_add3_u32 v174, v176, v174, s20
	v_bfe_u32 v175, v177, 16, 1
	v_lshrrev_b32_e32 v174, 16, v174
	v_add3_u32 v175, v177, v175, s20
	v_and_or_b32 v211, v175, s22, v174
	v_add_co_u32_e32 v174, vcc, s23, v206
	v_fma_f32 v195, v208, v18, 0
	s_nop 0
	v_addc_co_u32_e32 v175, vcc, 0, v207, vcc
	global_store_dwordx2 v[174:175], v[210:211], off
	v_fma_f32 v211, v208, v22, 0
	v_fmac_f32_e32 v195, v209, v26
	v_fmac_f32_e32 v211, v209, v30
	v_fmac_f32_e32 v195, v176, v34
	v_fmac_f32_e32 v211, v176, v38
	v_pk_mul_f32 v[170:171], v[196:197], v[170:171] op_sel_hi:[0,1]
	v_fmac_f32_e32 v195, v177, v42
	v_fmac_f32_e32 v211, v177, v46
	v_pk_mul_f32 v[170:171], v[170:171], v[10:11]
	v_pk_mul_f32 v[172:173], v[196:197], v[172:173] op_sel_hi:[0,1]
	v_fmac_f32_e32 v195, v170, v50
	v_fmac_f32_e32 v211, v170, v54
	v_pk_mul_f32 v[172:173], v[172:173], v[12:13]
	v_fmac_f32_e32 v195, v171, v58
	v_fmac_f32_e32 v211, v171, v62
	v_fma_f32 v206, v208, v19, 0
	v_fma_f32 v212, v208, v23, 0
	v_fmac_f32_e32 v195, v172, v66
	v_fmac_f32_e32 v211, v172, v70
	v_pk_mul_f32 v[166:167], v[196:197], v[166:167] op_sel_hi:[0,1]
	v_fma_f32 v207, v208, v20, 0
	v_fma_f32 v213, v208, v24, 0
	v_fmac_f32_e32 v206, v209, v27
	v_fmac_f32_e32 v212, v209, v31
	v_fmac_f32_e32 v195, v173, v74
	v_fmac_f32_e32 v211, v173, v78
	v_pk_mul_f32 v[166:167], v[166:167], v[6:7]
	v_fma_f32 v210, v208, v21, 0
	v_fma_f32 v208, v208, v25, 0
	v_fmac_f32_e32 v207, v209, v28
	v_fmac_f32_e32 v213, v209, v32
	v_fmac_f32_e32 v206, v176, v35
	v_fmac_f32_e32 v212, v176, v39
	v_pk_mul_f32 v[168:169], v[196:197], v[168:169] op_sel_hi:[0,1]
	v_fmac_f32_e32 v195, v166, v82
	v_fmac_f32_e32 v211, v166, v86
	v_fmac_f32_e32 v210, v209, v29
	v_fmac_f32_e32 v208, v209, v33
	v_fmac_f32_e32 v207, v176, v36
	v_fmac_f32_e32 v213, v176, v40
	v_fmac_f32_e32 v206, v177, v43
	v_fmac_f32_e32 v212, v177, v47
	v_pk_mul_f32 v[168:169], v[168:169], v[8:9]
	v_fmac_f32_e32 v195, v167, v90
	v_fmac_f32_e32 v211, v167, v94
	v_fmac_f32_e32 v210, v176, v37
	v_fmac_f32_e32 v208, v176, v41
	v_fmac_f32_e32 v207, v177, v44
	v_fmac_f32_e32 v213, v177, v48
	v_fmac_f32_e32 v206, v170, v51
	v_fmac_f32_e32 v212, v170, v55
	v_fmac_f32_e32 v195, v168, v98
	v_fmac_f32_e32 v211, v168, v102
	v_pk_mul_f32 v[162:163], v[196:197], v[162:163] op_sel_hi:[0,1]
	v_fmac_f32_e32 v210, v177, v45
	v_fmac_f32_e32 v208, v177, v49
	v_fmac_f32_e32 v207, v170, v52
	v_fmac_f32_e32 v213, v170, v56
	v_fmac_f32_e32 v206, v171, v59
	v_fmac_f32_e32 v212, v171, v63
	v_fmac_f32_e32 v195, v169, v106
	v_fmac_f32_e32 v211, v169, v110
	v_pk_mul_f32 v[162:163], v[162:163], v[2:3]
	v_fmac_f32_e32 v210, v170, v53
	v_fmac_f32_e32 v208, v170, v57
	v_fmac_f32_e32 v207, v171, v60
	v_fmac_f32_e32 v213, v171, v64
	v_fmac_f32_e32 v206, v172, v67
	v_fmac_f32_e32 v212, v172, v71
; #define LAS __attribute__((address_space(3)))
; __device__ __forceinline__ float log_sigmoid(float y) { return fminf(y, 0.f) - log1pf(expf(-fabsf(y))); }
; __global__ void __launch_bounds__(NWAVES * 64, 2) fwd_megakernel(Args args) {
;     ...
;                 for (int i = 0; i < 4; ++i) { const int k = 256 * j + 4 * lane + i; const f32x4 wa = *(const LAS f32x4*)(Wf + k * 8), wb = *(const LAS f32x4*)(Wf + k * 8 + 4); const float hk = v[j][i];
;                     fa[0] += hk * wa[0]; fa[1] += hk * wa[1]; fa[2] += hk * wa[2]; fa[3] += hk * wa[3]; fa[4] += hk * wb[0]; fa[5] += hk * wb[1]; fa[6] += hk * wb[2]; fa[7] += hk * wb[3]; } }
;             float r4[4], r2[2], r1;
;             { const bool h = (lane & 32) != 0;
; #pragma unroll
;               for (int e = 0; e < 4; ++e) { const float snd = h ? fa[e] : fa[e + 4], kp = h ? fa[e + 4] : fa[e]; r4[e] = kp + __shfl_xor(snd, 32); } }
;             { const bool h = (lane & 16) != 0;
; #pragma unroll
;               for (int e = 0; e < 2; ++e) { const float snd = h ? r4[e] : r4[e + 2], kp = h ? r4[e + 2] : r4[e]; r2[e] = kp + __shfl_xor(snd, 16); } }
;             { const bool h = (lane & 8) != 0; const float snd = h ? r2[0] : r2[1], kp = h ? r2[1] : r2[0]; r1 = kp + __shfl_xor(snd, 8); }
;             r1 += __shfl_xor(r1, 4); r1 += __shfl_xor(r1, 2); r1 += __shfl_xor(r1, 1);
;             if ((lane & 7) == 0) { const int e = lane >> 3; LF[(size_t)m * 8 + e] = log_sigmoid(r1 + fbias[e]); }
	v_pk_mul_f32 v[164:165], v[196:197], v[164:165] op_sel_hi:[0,1]
	v_fmac_f32_e32 v195, v162, v114
	v_fmac_f32_e32 v211, v162, v118
	v_fmac_f32_e32 v210, v171, v61
	v_fmac_f32_e32 v208, v171, v65
	v_fmac_f32_e32 v207, v172, v68
	v_fmac_f32_e32 v213, v172, v72
	v_fmac_f32_e32 v206, v173, v75
	v_fmac_f32_e32 v212, v173, v79
	v_pk_mul_f32 v[164:165], v[164:165], v[4:5]
	v_fmac_f32_e32 v195, v163, v122
	v_fmac_f32_e32 v211, v163, v126
	v_bfe_u32 v176, v170, 16, 1
	v_fmac_f32_e32 v210, v172, v69
	v_fmac_f32_e32 v208, v172, v73
	v_fmac_f32_e32 v207, v173, v76
	v_fmac_f32_e32 v213, v173, v80
	v_fmac_f32_e32 v206, v166, v83
	v_fmac_f32_e32 v212, v166, v87
	v_fmac_f32_e32 v195, v164, v130
	v_fmac_f32_e32 v211, v164, v134
	v_add3_u32 v176, v170, v176, s20
	v_fmac_f32_e32 v210, v173, v77
	v_fmac_f32_e32 v208, v173, v81
	v_bfe_u32 v170, v166, 16, 1
	v_fmac_f32_e32 v207, v166, v84
	v_fmac_f32_e32 v213, v166, v88
	v_fmac_f32_e32 v206, v167, v91
	v_fmac_f32_e32 v212, v167, v95
	v_fmac_f32_e32 v195, v165, v138
	v_fmac_f32_e32 v211, v165, v142
	v_add3_u32 v170, v166, v170, s20
	v_fmac_f32_e32 v210, v166, v85
	v_fmac_f32_e32 v208, v166, v89
	v_fmac_f32_e32 v207, v167, v92
	v_fmac_f32_e32 v213, v167, v96
	v_fmac_f32_e32 v206, v168, v99
	v_fmac_f32_e32 v212, v168, v103
	v_cndmask_b32_e64 v166, v195, v211, s[0:1]
	v_fmac_f32_e32 v210, v167, v93
	v_fmac_f32_e32 v208, v167, v97
	v_fmac_f32_e32 v207, v168, v100
	v_fmac_f32_e32 v213, v168, v104
	v_fmac_f32_e32 v206, v169, v107
	v_fmac_f32_e32 v212, v169, v111
	ds_bpermute_b32 v166, v201, v166
	v_bfe_u32 v177, v171, 16, 1
	v_fmac_f32_e32 v210, v168, v101
	v_fmac_f32_e32 v208, v168, v105
	v_fmac_f32_e32 v207, v169, v108
	v_fmac_f32_e32 v213, v169, v112
	v_fmac_f32_e32 v206, v162, v115
	v_fmac_f32_e32 v212, v162, v119
	v_lshrrev_b32_e32 v176, 16, v176
	v_add3_u32 v177, v171, v177, s20
	v_fmac_f32_e32 v210, v169, v109
	v_fmac_f32_e32 v208, v169, v113
	v_fmac_f32_e32 v207, v162, v116
	v_fmac_f32_e32 v213, v162, v120
	v_fmac_f32_e32 v206, v163, v123
	v_fmac_f32_e32 v212, v163, v127
	v_and_or_b32 v176, v177, s22, v176
	v_bfe_u32 v177, v172, 16, 1
	v_bfe_u32 v171, v167, 16, 1
	v_fmac_f32_e32 v210, v162, v117
	v_fmac_f32_e32 v208, v162, v121
	v_fmac_f32_e32 v207, v163, v124
	v_fmac_f32_e32 v213, v163, v128
	v_fmac_f32_e32 v206, v164, v131
	v_fmac_f32_e32 v212, v164, v135
	v_add3_u32 v177, v172, v177, s20
	v_bfe_u32 v209, v173, 16, 1
	v_add3_u32 v171, v167, v171, s20
	v_fmac_f32_e32 v210, v163, v125
	v_fmac_f32_e32 v208, v163, v129
	v_fmac_f32_e32 v207, v164, v132
	v_fmac_f32_e32 v213, v164, v136
	v_fmac_f32_e32 v206, v165, v139
	v_fmac_f32_e32 v212, v165, v143
	v_cndmask_b32_e64 v167, v211, v195, s[0:1]
	v_lshrrev_b32_e32 v177, 16, v177
	v_add3_u32 v209, v173, v209, s20
	v_fmac_f32_e32 v210, v164, v133
	v_fmac_f32_e32 v208, v164, v137
	v_fmac_f32_e32 v207, v165, v140
	v_fmac_f32_e32 v213, v165, v144
	s_waitcnt lgkmcnt(0)
	v_add_f32_e32 v166, v167, v166
	v_cndmask_b32_e64 v167, v206, v212, s[0:1]
	v_and_or_b32 v177, v209, s22, v177
	v_fmac_f32_e32 v210, v165, v141
	v_fmac_f32_e32 v208, v165, v145
	ds_bpermute_b32 v167, v201, v167
	v_cndmask_b32_e64 v173, v207, v213, s[0:1]
	global_store_dwordx2 v[174:175], v[176:177], off offset:512
	ds_bpermute_b32 v173, v201, v173
	v_cndmask_b32_e64 v176, v210, v208, s[0:1]
	v_lshrrev_b32_e32 v170, 16, v170
	ds_bpermute_b32 v176, v201, v176
	v_and_or_b32 v170, v171, s22, v170
	v_bfe_u32 v171, v168, 16, 1
	v_add3_u32 v171, v168, v171, s20
	v_cndmask_b32_e64 v168, v212, v206, s[0:1]
	s_waitcnt lgkmcnt(2)
	v_add_f32_e32 v167, v168, v167
	v_cndmask_b32_e64 v168, v213, v207, s[0:1]
	s_waitcnt lgkmcnt(1)
	v_add_f32_e32 v168, v168, v173
	v_cndmask_b32_e64 v173, v208, v210, s[0:1]
	s_waitcnt lgkmcnt(0)
	v_add_f32_e32 v173, v173, v176
	v_cndmask_b32_e64 v176, v166, v168, s[4:5]
	v_cndmask_b32_e64 v177, v167, v173, s[4:5]
	ds_bpermute_b32 v176, v200, v176
	ds_bpermute_b32 v177, v200, v177
	v_cndmask_b32_e64 v166, v168, v166, s[4:5]
	v_cndmask_b32_e64 v167, v173, v167, s[4:5]
	v_bfe_u32 v172, v169, 16, 1
	s_waitcnt lgkmcnt(1)
	v_add_f32_e32 v166, v166, v176
	s_waitcnt lgkmcnt(0)
	v_add_f32_e32 v167, v167, v177
	v_cndmask_b32_e64 v168, v166, v167, s[6:7]
	ds_bpermute_b32 v168, v199, v168
	v_cndmask_b32_e64 v166, v167, v166, s[6:7]
	v_lshrrev_b32_e32 v171, 16, v171
	v_add3_u32 v169, v169, v172, s20
	v_and_or_b32 v171, v169, s22, v171
	s_waitcnt lgkmcnt(0)
	v_add_f32_e32 v166, v166, v168
	ds_bpermute_b32 v167, v198, v166
	v_bfe_u32 v168, v163, 16, 1
	v_bfe_u32 v169, v162, 16, 1
	v_add3_u32 v163, v163, v168, s20
	v_add3_u32 v162, v162, v169, s20
	s_waitcnt lgkmcnt(0)
	v_add_f32_e32 v167, v166, v167
	ds_bpermute_b32 v168, v197, v167
	v_lshrrev_b32_e32 v162, 16, v162
	v_and_or_b32 v166, v163, s22, v162
	v_bfe_u32 v162, v164, 16, 1
	v_add3_u32 v162, v164, v162, s20
	v_lshrrev_b32_e32 v164, 16, v162
	s_waitcnt lgkmcnt(0)
	v_add_f32_e32 v162, v167, v168
	ds_bpermute_b32 v163, v179, v162
	v_bfe_u32 v167, v165, 16, 1
	v_add3_u32 v165, v165, v167, s20
	v_and_or_b32 v167, v165, s22, v164
	global_store_dwordx2 v[174:175], v[170:171], off offset:1024
	global_store_dwordx2 v[174:175], v[166:167], off offset:1536
	s_and_saveexec_b64 s[12:13], s[8:9]
	s_cbranch_execz .LBB0_173
; __device__ __forceinline__ float log_sigmoid(float y) { return fminf(y, 0.f) - log1pf(expf(-fabsf(y))); }
; __global__ void __launch_bounds__(NWAVES * 64, 2) fwd_megakernel(Args args) {
;     ...
;             if ((lane & 7) == 0) { const int e = lane >> 3; LF[(size_t)m * 8 + e] = log_sigmoid(r1 + fbias[e]); }
	s_waitcnt lgkmcnt(0)
	v_add_f32_e32 v162, v162, v163
	v_add_f32_e32 v162, v162, v214
	v_mul_f32_e64 v163, |v162|, s26
	v_fma_f32 v164, |v162|, s26, -v163
	v_rndne_f32_e32 v165, v163
	v_fma_f32 v164, |v162|, s27, v164
	v_sub_f32_e32 v163, v163, v165
	v_add_f32_e32 v163, v163, v164
	v_cvt_i32_f32_e32 v165, v165
	v_exp_f32_e32 v163, v163
	v_cmp_ngt_f32_e64 vcc, |v162|, s28
	v_min_f32_e32 v176, 0, v162
	v_ldexp_f32 v163, v163, v165
	v_cndmask_b32_e32 v163, 0, v163, vcc
	v_cmp_nlt_f32_e64 vcc, |v162|, s29
	s_nop 1
	v_cndmask_b32_e32 v177, v205, v163, vcc
	v_add_f32_e32 v164, 1.0, v177
	v_add_f32_e32 v165, -1.0, v164
	v_frexp_mant_f32_e32 v166, v164
	v_cvt_f64_f32_e32 v[162:163], v164
	v_sub_f32_e32 v167, v165, v164
	v_frexp_exp_i32_f64_e32 v162, v[162:163]
	v_cmp_gt_f32_e32 vcc, s31, v166
	v_sub_f32_e32 v165, v177, v165
	v_add_f32_e32 v163, 1.0, v167
	v_subbrev_co_u32_e32 v162, vcc, 0, v162, vcc
	v_add_f32_e32 v163, v165, v163
	v_sub_u32_e32 v165, 0, v162
	v_ldexp_f32 v164, v164, v165
	v_add_f32_e32 v166, -1.0, v164
	v_add_f32_e32 v167, 1.0, v164
	v_ldexp_f32 v163, v163, v165
	v_add_f32_e32 v165, 1.0, v166
	v_add_f32_e32 v168, -1.0, v167
	v_sub_f32_e32 v165, v164, v165
	v_sub_f32_e32 v164, v164, v168
	v_add_f32_e32 v168, v163, v165
	v_add_f32_e32 v163, v163, v164
	v_add_f32_e32 v170, v167, v163
	v_rcp_f32_e32 v171, v170
	v_add_f32_e32 v165, v166, v168
	v_sub_f32_e32 v166, v166, v165
	v_sub_f32_e32 v164, v167, v170
	v_mul_f32_e32 v173, v165, v171
	v_add_f32_e32 v172, v168, v166
	v_mul_f32_e32 v166, v170, v173
	v_add_f32_e32 v163, v163, v164
	v_fma_f32 v168, v173, v170, -v166
	v_fmac_f32_e32 v168, v173, v163
	v_add_f32_e32 v164, v166, v168
	v_sub_f32_e32 v167, v165, v164
	v_mov_b32_e32 v169, v164
	v_pk_add_f32 v[164:165], v[164:165], v[166:167] neg_lo:[0,1] neg_hi:[0,1]
	v_cvt_f32_i32_e32 v162, v162
	v_pk_add_f32 v[164:165], v[164:165], v[168:169] neg_lo:[0,1] neg_hi:[0,1]
	v_cmp_neq_f32_e32 vcc, s30, v177
	v_add_f32_e32 v165, v172, v165
	v_add_f32_e32 v164, v164, v165
	v_add_f32_e32 v165, v167, v164
	v_mul_f32_e32 v169, v171, v165
	v_mul_f32_e32 v166, v170, v169
	v_sub_f32_e32 v167, v167, v165
	v_add_f32_e32 v174, v173, v169
	v_fma_f32 v168, v169, v170, -v166
	v_add_f32_e32 v172, v164, v167
	v_sub_f32_e32 v164, v174, v173
	v_fmac_f32_e32 v168, v169, v163
	v_sub_f32_e32 v163, v169, v164
	v_add_f32_e32 v164, v166, v168
	v_sub_f32_e32 v167, v165, v164
	v_mov_b32_e32 v169, v164
	v_pk_add_f32 v[164:165], v[164:165], v[166:167] neg_lo:[0,1] neg_hi:[0,1]
	s_nop 0
	v_pk_add_f32 v[164:165], v[164:165], v[168:169] neg_lo:[0,1] neg_hi:[0,1]
	s_nop 0
	v_add_f32_e32 v165, v172, v165
	v_add_f32_e32 v164, v164, v165
	v_add_f32_e32 v164, v167, v164
	v_mul_f32_e32 v164, v171, v164
	v_add_f32_e32 v163, v163, v164
	v_add_f32_e32 v164, v174, v163
	v_mul_f32_e32 v166, v164, v164
	v_sub_f32_e32 v167, v164, v174
	v_fmamk_f32 v168, v166, 0x3e9b6dac, v204
	v_sub_f32_e32 v167, v163, v167
	v_mul_f32_e32 v163, v164, v166
	v_fmaak_f32 v195, v166, v168, 0x3f2aaada
	v_ldexp_f32 v169, v167, 1
	v_pk_mul_f32 v[166:167], v[162:163], v[194:195]
	v_ldexp_f32 v165, v164, 1
	v_fma_f32 v164, v162, s33, -v166
	v_fmac_f32_e32 v164, 0xb102e308, v162
	v_pk_add_f32 v[162:163], v[166:167], v[164:165]
	v_mov_b32_e32 v168, v166
	v_sub_f32_e32 v172, v163, v165
	v_pk_add_f32 v[170:171], v[162:163], v[166:167] neg_lo:[0,1] neg_hi:[0,1]
	v_sub_f32_e32 v166, v167, v172
	v_add_f32_e32 v169, v169, v166
	v_pk_add_f32 v[166:167], v[162:163], v[168:169]
	v_mov_b32_e32 v165, v162
	v_mov_b32_e32 v171, v167
	v_pk_add_f32 v[174:175], v[164:165], v[170:171] neg_lo:[0,1] neg_hi:[0,1]
	v_pk_add_f32 v[164:165], v[164:165], v[170:171]
	v_mov_b32_e32 v173, v162
	v_pk_add_f32 v[170:171], v[164:165], v[162:163] op_sel:[1,0] op_sel_hi:[0,1] neg_lo:[0,1] neg_hi:[0,1]
	v_mov_b32_e32 v172, v169
	v_mov_b32_e32 v168, v167
	v_mov_b32_e32 v169, v165
	v_pk_mov_b32 v[162:163], v[162:163], v[170:171] op_sel:[1,0]
	v_pk_add_f32 v[166:167], v[166:167], v[170:171] op_sel_hi:[1,0] neg_lo:[0,1] neg_hi:[0,1]
	v_pk_add_f32 v[162:163], v[168:169], v[162:163] neg_lo:[0,1] neg_hi:[0,1]
	v_mov_b32_e32 v166, v174
	v_pk_add_f32 v[162:163], v[172:173], v[162:163] neg_lo:[0,1] neg_hi:[0,1]
	v_mov_b32_e32 v175, v165
	v_pk_add_f32 v[166:167], v[166:167], v[162:163]
	s_nop 0
	v_pk_add_f32 v[168:169], v[166:167], v[166:167] op_sel:[0,1] op_sel_hi:[1,0]
	s_nop 0
	v_pk_add_f32 v[164:165], v[164:165], v[168:169] op_sel:[1,0] op_sel_hi:[0,1]
	v_mov_b32_e32 v167, v164
	v_mov_b32_e32 v163, v168
	v_pk_add_f32 v[168:169], v[166:167], v[174:175] neg_lo:[0,1] neg_hi:[0,1]
	s_nop 0
	v_sub_f32_e32 v165, v166, v168
	v_pk_add_f32 v[162:163], v[162:163], v[168:169] neg_lo:[0,1] neg_hi:[0,1]
	v_sub_f32_e32 v165, v174, v165
	v_add_f32_e32 v162, v162, v165
	v_add_f32_e32 v162, v162, v163
	v_add_f32_e32 v162, v164, v162
	v_cndmask_b32_e32 v162, v205, v162, vcc
	v_cmp_lt_f32_e64 vcc, |v177|, s34
	s_nop 1
	v_cndmask_b32_e32 v162, v162, v177, vcc
	v_sub_f32_e32 v164, v176, v162
	v_lshl_add_u64 v[162:163], s[66:67], 0, v[188:189]
	global_store_dword v[162:163], v164, off
	s_branch .LBB0_173
